# first arriver of each XCD issues an early un-waited L2 write-back before polling
# baseline (speedup 1.0000x reference)
.Lmy_xb4_have:
	v_mov_b32_e32 v0, s9
	v_mov_b32_e32 v4, 1
	global_atomic_add v4, v0, v4, s[36:37] sc0
	v_cvt_f32_u32_e32 v5, v3
	v_rcp_f32_e32 v5, v5
	s_waitcnt vmcnt(0)
	v_cvt_f32_u32_e32 v0, v4
	v_add_f32_e32 v0, 0.5, v0
	v_mul_f32_e32 v0, v0, v5
	v_cvt_u32_f32_e32 v0, v0
	v_add_u32_e32 v0, 1, v0
	v_mul_lo_u32 v5, v0, v3
	v_mul_lo_u32 v2, v0, v2
	v_add_u32_e32 v4, 1, v4
	v_mov_b32_e32 v0, s10
	v_cmp_ne_u32_e32 vcc, v4, v5
	s_cbranch_vccz .Lmy_xb4_lead
	v_sub_u32_e32 v5, v5, v3
	v_add_u32_e32 v5, 1, v5
	v_cmp_ne_u32_e32 vcc, v4, v5
	s_cbranch_vccnz .Lmy_xb4_poll
	buffer_wbl2 sc1
	s_branch .Lmy_xb4_poll
.Lmy_xb4_lead:
	buffer_wbl2 sc1
	s_waitcnt vmcnt(0)
	v_mov_b32_e32 v4, 1
	v_mov_b32_e32 v3, 0x4000
	global_atomic_add v3, v4, s[36:37]
	v_mov_b32_e32 v3, 0x4100
	global_atomic_add v3, v4, s[36:37]
	v_mov_b32_e32 v3, 0x4200
	global_atomic_add v3, v4, s[36:37]
	v_mov_b32_e32 v3, 0x4300
	global_atomic_add v3, v4, s[36:37]
	v_mov_b32_e32 v3, 0x4400
	global_atomic_add v3, v4, s[36:37]
	v_mov_b32_e32 v3, 0x4500
	global_atomic_add v3, v4, s[36:37]
	v_mov_b32_e32 v3, 0x4600
	global_atomic_add v3, v4, s[36:37]
	v_mov_b32_e32 v3, 0x4700
	global_atomic_add v3, v4, s[36:37]
	v_mov_b32_e32 v3, 0x4800
	global_atomic_add v3, v4, s[36:37]
	v_mov_b32_e32 v3, 0x4900
	global_atomic_add v3, v4, s[36:37]
	v_mov_b32_e32 v3, 0x4a00
	global_atomic_add v3, v4, s[36:37]
	v_mov_b32_e32 v3, 0x4b00
	global_atomic_add v3, v4, s[36:37]
	v_mov_b32_e32 v3, 0x4c00
	global_atomic_add v3, v4, s[36:37]
	v_mov_b32_e32 v3, 0x4d00
	global_atomic_add v3, v4, s[36:37]
	v_mov_b32_e32 v3, 0x4e00
	global_atomic_add v3, v4, s[36:37]
	v_mov_b32_e32 v3, 0x4f00
	global_atomic_add v3, v4, s[36:37]

.LBB0_489:
	s_getreg_b32 s6, hwreg(HW_REG_XCC_ID, 0, 4)
	s_waitcnt vmcnt(0)
	s_barrier
	s_and_saveexec_b64 s[4:5], s[74:75]
	s_cbranch_execz .LBB0_541
	v_readlane_b32 s7, v255, 10
	v_readlane_b32 s8, v255, 11
	s_and_b32 s6, s6, 15
	s_lshl_b32 s6, s6, 8
	v_mov_b32_e32 v0, s7
	v_mov_b32_e32 v2, s8
	ds_read_b32 v3, v0
	ds_read_b32 v2, v2
	s_add_i32 s9, s6, 0x1400
	s_add_i32 s10, s6, 0x4000
	s_waitcnt vmcnt(0) lgkmcnt(0)
	v_mov_b32_e32 v0, s9
	v_mov_b32_e32 v4, 1
	global_atomic_add v4, v0, v4, s[36:37] sc0
	v_cvt_f32_u32_e32 v5, v3
	v_rcp_f32_e32 v5, v5
	s_waitcnt vmcnt(0)
	v_cvt_f32_u32_e32 v0, v4
	v_add_f32_e32 v0, 0.5, v0
	v_mul_f32_e32 v0, v0, v5
	v_cvt_u32_f32_e32 v0, v0
	v_add_u32_e32 v0, 1, v0
	v_mul_lo_u32 v5, v0, v3
	v_mul_lo_u32 v2, v0, v2
	v_add_u32_e32 v4, 1, v4
	v_mov_b32_e32 v0, s10
	v_cmp_ne_u32_e32 vcc, v4, v5
	s_cbranch_vccz .Lmy_xb0_lead
	v_sub_u32_e32 v5, v5, v3
	v_add_u32_e32 v5, 1, v5
	v_cmp_ne_u32_e32 vcc, v4, v5
	s_cbranch_vccnz .Lmy_xb0_poll
	buffer_wbl2 sc1
	s_branch .Lmy_xb0_poll

.LBB0_974:
	s_getreg_b32 s6, hwreg(HW_REG_XCC_ID, 0, 4)
	s_waitcnt vmcnt(0)
	s_waitcnt lgkmcnt(0)
	s_barrier
	s_and_saveexec_b64 s[4:5], s[74:75]
	s_cbranch_execz .LBB0_1026
	v_readlane_b32 s7, v255, 10
	v_readlane_b32 s8, v255, 11
	s_and_b32 s6, s6, 15
	s_lshl_b32 s6, s6, 8
	v_mov_b32_e32 v0, s7
	v_mov_b32_e32 v2, s8
	ds_read_b32 v3, v0
	ds_read_b32 v2, v2
	s_add_i32 s9, s6, 0x1400
	s_add_i32 s10, s6, 0x4000
	s_waitcnt vmcnt(0) lgkmcnt(0)
	v_mov_b32_e32 v0, s9
	v_mov_b32_e32 v4, 1
	global_atomic_add v4, v0, v4, s[36:37] sc0
	v_cvt_f32_u32_e32 v5, v3
	v_rcp_f32_e32 v5, v5
	s_waitcnt vmcnt(0)
	v_cvt_f32_u32_e32 v0, v4
	v_add_f32_e32 v0, 0.5, v0
	v_mul_f32_e32 v0, v0, v5
	v_cvt_u32_f32_e32 v0, v0
	v_add_u32_e32 v0, 1, v0
	v_mul_lo_u32 v5, v0, v3
	v_mul_lo_u32 v2, v0, v2
	v_add_u32_e32 v4, 1, v4
	v_mov_b32_e32 v0, s10
	v_cmp_ne_u32_e32 vcc, v4, v5
	s_cbranch_vccz .Lmy_xb2_lead
	v_sub_u32_e32 v5, v5, v3
	v_add_u32_e32 v5, 1, v5
	v_cmp_ne_u32_e32 vcc, v4, v5
	s_cbranch_vccnz .Lmy_xb2_poll
	buffer_wbl2 sc1
	s_branch .Lmy_xb2_poll

.LBB0_1186:
	s_cmp_eq_u32 s40, 7
	v_readlane_b32 s26, v255, 37
	v_readlane_b32 s27, v255, 38
	s_cbranch_scc1 .LBB0_161
	s_getreg_b32 s6, hwreg(HW_REG_XCC_ID, 0, 4)
	s_waitcnt vmcnt(0)
	s_barrier
	s_and_saveexec_b64 s[4:5], s[74:75]
	s_cbranch_execz .LBB0_160
	v_readlane_b32 s7, v255, 10
	v_readlane_b32 s8, v255, 11
	s_and_b32 s6, s6, 15
	s_lshl_b32 s6, s6, 8
	v_mov_b32_e32 v0, s7
	v_mov_b32_e32 v2, s8
	ds_read_b32 v3, v0
	ds_read_b32 v2, v2
	s_add_i32 s9, s6, 0x1400
	s_add_i32 s10, s6, 0x4000
	s_waitcnt vmcnt(0) lgkmcnt(0)
	v_mov_b32_e32 v0, s9
	v_mov_b32_e32 v4, 1
	global_atomic_add v4, v0, v4, s[36:37] sc0
	v_cvt_f32_u32_e32 v5, v3
	v_rcp_f32_e32 v5, v5
	s_waitcnt vmcnt(0)
	v_cvt_f32_u32_e32 v0, v4
	v_add_f32_e32 v0, 0.5, v0
	v_mul_f32_e32 v0, v0, v5
	v_cvt_u32_f32_e32 v0, v0
	v_add_u32_e32 v0, 1, v0
	v_mul_lo_u32 v5, v0, v3
	v_mul_lo_u32 v2, v0, v2
	v_add_u32_e32 v4, 1, v4
	v_mov_b32_e32 v0, s10
	v_cmp_ne_u32_e32 vcc, v4, v5
	s_cbranch_vccz .Lmy_xb3_lead
	v_sub_u32_e32 v5, v5, v3
	v_add_u32_e32 v5, 1, v5
	v_cmp_ne_u32_e32 vcc, v4, v5
	s_cbranch_vccnz .Lmy_xb3_poll
	buffer_wbl2 sc1
	s_branch .Lmy_xb3_poll
